# FFN-down GEMM K-loop: LDS-DMA issue rebalanced to 4 per super-phase (A half-tile staged one super-phase later), on top of attention reschedule
# baseline (speedup 1.0000x reference)
; #define PG8_STAGE(bufoff, gbase, voff) do { _Pragma("unroll") for (int _i = 0; _i < 2; ++_i) \
;         __builtin_amdgcn_global_load_lds((const unsigned*)((const char*)(gbase) + (voff)[_i]), (PG8_LAS unsigned*)(lds + (bufoff) + ldsw + _i * 8192), 16, 0, 0); } while (0)
; #define PG8_LDA(dst, b, h) do { _Pragma("unroll") for (int m = 0; m < 4; ++m) _Pragma("unroll") for (int k = 0; k < 2; ++k) dst[m][k] = *(const PG8_LAS bf16x8*)(lds + PG8_SA(b, h) + aoff + m * 2048 + k * 1024); } while (0)
; #define PG8_LDB(dst, b, h) do { _Pragma("unroll") for (int n = 0; n < 2; ++n) _Pragma("unroll") for (int k = 0; k < 2; ++k) dst[n][k] = *(const PG8_LAS bf16x8*)(lds + PG8_SB(b, h) + boff + n * 2048 + k * 1024); } while (0)
; #define PG8_MMA(ai, bj, At, Bt) do { __builtin_amdgcn_s_setprio(1); _Pragma("unroll") for (int m = 0; m < 4; ++m) _Pragma("unroll") for (int n = 0; n < 2; ++n) _Pragma("unroll") for (int k = 0; k < 2; ++k) \
;         acc[ai][bj][m][n] = __builtin_amdgcn_mfma_f32_16x16x32_bf16(Bt[n][k], At[m][k], acc[ai][bj][m][n], 0, 0, 0); __builtin_amdgcn_s_setprio(0); } while (0)
; #define PG8_WAIT_V(n) asm volatile("s_waitcnt vmcnt(" #n ")" ::: "memory")
; #define PG8_WAIT_L(n) asm volatile("s_waitcnt lgkmcnt(" #n ")" ::: "memory")
; #define PG8_BAR __builtin_amdgcn_s_barrier()
; #define PG8_SCHED __builtin_amdgcn_sched_barrier(0)
; template <class Epi, class Sched, bool ALIGN_EPI = false, bool SP2 = false, bool AROWS128 = false>
; __device__ __forceinline__ void gemm_phase(PG8_LAS unsigned char* lds, const Gemm g, const Sched& S, const Epi& E) {
;     ...
;             PG8_LDB(B0, 0, 0); PG8_LDB(B1, 0, 1); PG8_SCHED; PG8_LDA(At, 0, 0); PG8_STAGE(PG8_SA(1, 1), a1 + hstepA, voffA);
;             PG8_WAIT_V(8); PG8_WAIT_L(0); PG8_BAR; PG8_MMA(0, 0, At, B0); PG8_MMA(0, 1, At, B1); PG8_BAR; PG8_SCHED;
;             PG8_LDA(At, 0, 1); PG8_STAGE(PG8_SB(0, 0), b2, voffB); PG8_STAGE(PG8_SB(0, 1), b2 + hstep, voffB); PG8_STAGE(PG8_SA(0, 0), a2, voffA);
.LBB0_752:
	ds_read_b128 v[152:155], v149
	ds_read_b128 v[156:159], v149 offset:1024
	ds_read_b128 v[160:163], v149 offset:2048
	ds_read_b128 v[164:167], v149 offset:3072
	ds_read_b128 v[168:171], v150
	ds_read_b128 v[172:175], v150 offset:1024
	ds_read_b128 v[176:179], v150 offset:2048
	ds_read_b128 v[180:183], v150 offset:3072
	s_add_u32 s38, s36, 0xfff00080
	s_addc_u32 s39, s37, -1
	s_add_u32 s98, s36, 0xfff00000
	s_addc_u32 s99, s37, -1
	s_cmp_eq_u32 s77, 60
	s_cselect_b32 s49, s25, s39
	s_cselect_b32 s48, s65, s38
	s_cselect_b32 s39, s21, s76
	s_cselect_b32 s38, s72, s73
	v_lshl_add_u64 v[144:145], s[98:99], 0, v[134:135]
	s_mov_b32 m0, s54
	s_nop 0
	global_load_lds_dwordx4 v[144:145], off
	v_lshl_add_u64 v[144:145], s[98:99], 0, v[130:131]
	s_mov_b32 m0, s55
	s_nop 0
	global_load_lds_dwordx4 v[144:145], off
	v_lshl_add_u64 v[144:145], s[36:37], 0, v[136:137]
	s_add_i32 m0, s31, 0xc000
	ds_read_b128 v[184:187], v151
	ds_read_b128 v[188:191], v151 offset:1024
	ds_read_b128 v[192:195], v151 offset:2048
	ds_read_b128 v[196:199], v151 offset:3072
	ds_read_b128 v[200:203], v151 offset:4096
	ds_read_b128 v[204:207], v151 offset:5120
	ds_read_b128 v[212:215], v151 offset:6144
	ds_read_b128 v[216:219], v151 offset:7168
	global_load_lds_dwordx4 v[144:145], off
	v_lshl_add_u64 v[144:145], s[36:37], 0, v[138:139]
	s_add_i32 m0, s31, 0xe000
	s_nop 0
	global_load_lds_dwordx4 v[144:145], off
	s_waitcnt vmcnt(8)
	s_waitcnt lgkmcnt(0)
	s_barrier
	s_setprio 1
	s_waitcnt lgkmcnt(0)
	v_mfma_f32_16x16x32_bf16 v[124:127], v[152:155], v[184:187], v[124:127]
	v_mfma_f32_16x16x32_bf16 v[120:123], v[160:163], v[184:187], v[120:123]
	v_mfma_f32_16x16x32_bf16 v[116:119], v[152:155], v[192:195], v[116:119]
	v_mfma_f32_16x16x32_bf16 v[108:111], v[160:163], v[192:195], v[108:111]
	v_mfma_f32_16x16x32_bf16 v[100:103], v[152:155], v[200:203], v[100:103]
	v_mfma_f32_16x16x32_bf16 v[92:95], v[160:163], v[200:203], v[92:95]
	v_mfma_f32_16x16x32_bf16 v[84:87], v[152:155], v[212:215], v[84:87]
	v_mfma_f32_16x16x32_bf16 v[76:79], v[160:163], v[212:215], v[76:79]
	v_mfma_f32_16x16x32_bf16 v[124:127], v[156:159], v[188:191], v[124:127]
	v_mfma_f32_16x16x32_bf16 v[120:123], v[164:167], v[188:191], v[120:123]
	v_mfma_f32_16x16x32_bf16 v[116:119], v[156:159], v[196:199], v[116:119]
	v_mfma_f32_16x16x32_bf16 v[108:111], v[164:167], v[196:199], v[108:111]
	v_mfma_f32_16x16x32_bf16 v[100:103], v[156:159], v[204:207], v[100:103]
	v_mfma_f32_16x16x32_bf16 v[92:95], v[164:167], v[204:207], v[92:95]
	v_mfma_f32_16x16x32_bf16 v[84:87], v[156:159], v[216:219], v[84:87]
	v_mfma_f32_16x16x32_bf16 v[76:79], v[164:167], v[216:219], v[76:79]
	s_setprio 0
	s_setprio 1
	v_mfma_f32_16x16x32_bf16 v[112:115], v[168:171], v[184:187], v[112:115]
	v_mfma_f32_16x16x32_bf16 v[104:107], v[176:179], v[184:187], v[104:107]
	v_mfma_f32_16x16x32_bf16 v[96:99], v[168:171], v[192:195], v[96:99]
	v_mfma_f32_16x16x32_bf16 v[88:91], v[176:179], v[192:195], v[88:91]
	v_mfma_f32_16x16x32_bf16 v[80:83], v[168:171], v[200:203], v[80:83]
	v_mfma_f32_16x16x32_bf16 v[72:75], v[176:179], v[200:203], v[72:75]
	v_mfma_f32_16x16x32_bf16 v[68:71], v[168:171], v[212:215], v[68:71]
	v_mfma_f32_16x16x32_bf16 v[64:67], v[176:179], v[212:215], v[64:67]
	v_mfma_f32_16x16x32_bf16 v[112:115], v[172:175], v[188:191], v[112:115]
	v_mfma_f32_16x16x32_bf16 v[104:107], v[180:183], v[188:191], v[104:107]
	v_mfma_f32_16x16x32_bf16 v[96:99], v[172:175], v[196:199], v[96:99]
	v_mfma_f32_16x16x32_bf16 v[88:91], v[180:183], v[196:199], v[88:91]
	v_mfma_f32_16x16x32_bf16 v[80:83], v[172:175], v[204:207], v[80:83]
	v_mfma_f32_16x16x32_bf16 v[72:75], v[180:183], v[204:207], v[72:75]
	v_mfma_f32_16x16x32_bf16 v[68:71], v[172:175], v[216:219], v[68:71]
	v_mfma_f32_16x16x32_bf16 v[64:67], v[180:183], v[216:219], v[64:67]
	s_setprio 0
	s_barrier
	s_add_i32 s78, s58, s3
	v_lshl_add_u64 v[144:145], s[38:39], 0, v[132:133]
	s_mov_b32 m0, s78
	ds_read_b128 v[184:187], v151 offset:16384
	ds_read_b128 v[188:191], v151 offset:17408
	ds_read_b128 v[192:195], v151 offset:18432
	ds_read_b128 v[196:199], v151 offset:19456
	ds_read_b128 v[200:203], v151 offset:20480
	ds_read_b128 v[204:207], v151 offset:21504
	ds_read_b128 v[212:215], v151 offset:22528
	ds_read_b128 v[216:219], v151 offset:23552
	global_load_lds_dwordx4 v[144:145], off
	s_add_i32 m0, s78, 0x2000
	s_add_u32 s78, s38, 0x100000
	v_lshl_add_u64 v[208:209], s[38:39], 0, v[128:129]
	s_addc_u32 s79, s39, 0
	s_add_i32 s80, s59, s3
	global_load_lds_dwordx4 v[208:209], off
	v_lshl_add_u64 v[220:221], s[78:79], 0, v[132:133]
	s_mov_b32 m0, s80
	v_lshl_add_u64 v[222:223], s[48:49], 0, v[130:131]
	global_load_lds_dwordx4 v[220:221], off
	v_lshl_add_u64 v[220:221], s[78:79], 0, v[128:129]
	s_add_i32 m0, s80, 0x2000
	s_nop 0
	global_load_lds_dwordx4 v[220:221], off
	s_waitcnt vmcnt(6)
	s_waitcnt lgkmcnt(0)
	s_barrier
; #define PG8_STAGE(bufoff, gbase, voff) do { _Pragma("unroll") for (int _i = 0; _i < 2; ++_i) \
;         __builtin_amdgcn_global_load_lds((const unsigned*)((const char*)(gbase) + (voff)[_i]), (PG8_LAS unsigned*)(lds + (bufoff) + ldsw + _i * 8192), 16, 0, 0); } while (0)
; #define PG8_LDA(dst, b, h) do { _Pragma("unroll") for (int m = 0; m < 4; ++m) _Pragma("unroll") for (int k = 0; k < 2; ++k) dst[m][k] = *(const PG8_LAS bf16x8*)(lds + PG8_SA(b, h) + aoff + m * 2048 + k * 1024); } while (0)
; #define PG8_LDB(dst, b, h) do { _Pragma("unroll") for (int n = 0; n < 2; ++n) _Pragma("unroll") for (int k = 0; k < 2; ++k) dst[n][k] = *(const PG8_LAS bf16x8*)(lds + PG8_SB(b, h) + boff + n * 2048 + k * 1024); } while (0)
; #define PG8_MMA(ai, bj, At, Bt) do { __builtin_amdgcn_s_setprio(1); _Pragma("unroll") for (int m = 0; m < 4; ++m) _Pragma("unroll") for (int n = 0; n < 2; ++n) _Pragma("unroll") for (int k = 0; k < 2; ++k) \
;         acc[ai][bj][m][n] = __builtin_amdgcn_mfma_f32_16x16x32_bf16(Bt[n][k], At[m][k], acc[ai][bj][m][n], 0, 0, 0); __builtin_amdgcn_s_setprio(0); } while (0)
; #define PG8_WAIT_V(n) asm volatile("s_waitcnt vmcnt(" #n ")" ::: "memory")
; #define PG8_WAIT_L(n) asm volatile("s_waitcnt lgkmcnt(" #n ")" ::: "memory")
; #define PG8_BAR __builtin_amdgcn_s_barrier()
; #define PG8_SCHED __builtin_amdgcn_sched_barrier(0)
; template <class Epi, class Sched, bool ALIGN_EPI = false, bool SP2 = false, bool AROWS128 = false>
; __device__ __forceinline__ void gemm_phase(PG8_LAS unsigned char* lds, const Gemm g, const Sched& S, const Epi& E) {
;     ...
;             PG8_WAIT_V(8); PG8_WAIT_L(0); PG8_BAR; PG8_MMA(1, 0, At, B0); PG8_MMA(1, 1, At, B1); PG8_BAR; PG8_SCHED;
;             PG8_LDB(B0, 1, 0); PG8_LDB(B1, 1, 1); PG8_SCHED; PG8_LDA(At, 1, 0); PG8_STAGE(PG8_SA(0, 1), a2 + hstepA, voffA);
;             PG8_WAIT_V(8); PG8_WAIT_L(0); PG8_BAR; PG8_MMA(0, 0, At, B0); PG8_MMA(0, 1, At, B1); PG8_BAR; PG8_SCHED;
	s_setprio 1
	s_waitcnt lgkmcnt(0)
	v_mfma_f32_16x16x32_bf16 v[60:63], v[152:155], v[184:187], v[60:63]
	v_mfma_f32_16x16x32_bf16 v[56:59], v[160:163], v[184:187], v[56:59]
	v_mfma_f32_16x16x32_bf16 v[52:55], v[152:155], v[192:195], v[52:55]
	v_mfma_f32_16x16x32_bf16 v[44:47], v[160:163], v[192:195], v[44:47]
	v_mfma_f32_16x16x32_bf16 v[36:39], v[152:155], v[200:203], v[36:39]
	v_mfma_f32_16x16x32_bf16 v[28:31], v[160:163], v[200:203], v[28:31]
	v_mfma_f32_16x16x32_bf16 v[20:23], v[152:155], v[212:215], v[20:23]
	v_mfma_f32_16x16x32_bf16 v[12:15], v[160:163], v[212:215], v[12:15]
	v_mfma_f32_16x16x32_bf16 v[60:63], v[156:159], v[188:191], v[60:63]
	v_mfma_f32_16x16x32_bf16 v[56:59], v[164:167], v[188:191], v[56:59]
	v_mfma_f32_16x16x32_bf16 v[52:55], v[156:159], v[196:199], v[52:55]
	v_mfma_f32_16x16x32_bf16 v[44:47], v[164:167], v[196:199], v[44:47]
	v_mfma_f32_16x16x32_bf16 v[36:39], v[156:159], v[204:207], v[36:39]
	v_mfma_f32_16x16x32_bf16 v[28:31], v[164:167], v[204:207], v[28:31]
	v_mfma_f32_16x16x32_bf16 v[20:23], v[156:159], v[216:219], v[20:23]
	v_mfma_f32_16x16x32_bf16 v[12:15], v[164:167], v[216:219], v[12:15]
	s_setprio 0
	s_setprio 1
	v_mfma_f32_16x16x32_bf16 v[48:51], v[168:171], v[184:187], v[48:51]
	v_mfma_f32_16x16x32_bf16 v[40:43], v[176:179], v[184:187], v[40:43]
	v_mfma_f32_16x16x32_bf16 v[32:35], v[168:171], v[192:195], v[32:35]
	v_mfma_f32_16x16x32_bf16 v[24:27], v[176:179], v[192:195], v[24:27]
	v_mfma_f32_16x16x32_bf16 v[16:19], v[168:171], v[200:203], v[16:19]
	v_mfma_f32_16x16x32_bf16 v[8:11], v[176:179], v[200:203], v[8:11]
	v_mfma_f32_16x16x32_bf16 v[4:7], v[168:171], v[212:215], v[4:7]
	v_mfma_f32_16x16x32_bf16 v[0:3], v[176:179], v[212:215], v[0:3]
	v_mfma_f32_16x16x32_bf16 v[48:51], v[172:175], v[188:191], v[48:51]
	v_mfma_f32_16x16x32_bf16 v[40:43], v[180:183], v[188:191], v[40:43]
	v_mfma_f32_16x16x32_bf16 v[32:35], v[172:175], v[196:199], v[32:35]
	v_mfma_f32_16x16x32_bf16 v[24:27], v[180:183], v[196:199], v[24:27]
	v_mfma_f32_16x16x32_bf16 v[16:19], v[172:175], v[204:207], v[16:19]
	v_mfma_f32_16x16x32_bf16 v[8:11], v[180:183], v[204:207], v[8:11]
	v_mfma_f32_16x16x32_bf16 v[4:7], v[172:175], v[216:219], v[4:7]
	v_mfma_f32_16x16x32_bf16 v[0:3], v[180:183], v[216:219], v[0:3]
	s_setprio 0
	s_barrier
	s_add_i32 s78, 0, 0x18000
	s_add_i32 s79, 0, 0x1c000
	v_add_u32_e32 v164, s78, v147
	v_add_u32_e32 v180, s79, v147
	ds_read_b128 v[152:155], v164
	ds_read_b128 v[156:159], v164 offset:1024
	ds_read_b128 v[160:163], v164 offset:2048
	ds_read_b128 v[164:167], v164 offset:3072
	ds_read_b128 v[168:171], v180
	ds_read_b128 v[172:175], v180 offset:1024
	ds_read_b128 v[176:179], v180 offset:2048
	ds_read_b128 v[180:183], v180 offset:3072
	v_lshl_add_u64 v[224:225], s[48:49], 0, v[134:135]
	s_mov_b32 m0, s31
	s_nop 0
	global_load_lds_dwordx4 v[224:225], off
	v_lshl_add_u64 v[224:225], s[48:49], 0, v[130:131]
	s_mov_b32 m0, s50
	s_nop 0
	global_load_lds_dwordx4 v[224:225], off
	s_add_u32 s48, s48, 0x100000
	s_addc_u32 s49, s49, 0
	s_mov_b32 m0, s51
	v_lshl_add_u64 v[224:225], s[48:49], 0, v[134:135]
	ds_read_b128 v[184:187], v151 offset:32768
	ds_read_b128 v[188:191], v151 offset:33792
	ds_read_b128 v[192:195], v151 offset:34816
	ds_read_b128 v[196:199], v151 offset:35840
	ds_read_b128 v[200:203], v151 offset:36864
	ds_read_b128 v[204:207], v151 offset:37888
	ds_read_b128 v[212:215], v151 offset:38912
	ds_read_b128 v[216:219], v151 offset:39936
	global_load_lds_dwordx4 v[224:225], off
	v_lshl_add_u64 v[224:225], s[48:49], 0, v[130:131]
	s_mov_b32 m0, s52
	s_nop 0
	global_load_lds_dwordx4 v[224:225], off
	s_waitcnt vmcnt(8)
	s_waitcnt lgkmcnt(0)
	s_barrier
; #define PG8_STAGE(bufoff, gbase, voff) do { _Pragma("unroll") for (int _i = 0; _i < 2; ++_i) \
;         __builtin_amdgcn_global_load_lds((const unsigned*)((const char*)(gbase) + (voff)[_i]), (PG8_LAS unsigned*)(lds + (bufoff) + ldsw + _i * 8192), 16, 0, 0); } while (0)
; #define PG8_LDA(dst, b, h) do { _Pragma("unroll") for (int m = 0; m < 4; ++m) _Pragma("unroll") for (int k = 0; k < 2; ++k) dst[m][k] = *(const PG8_LAS bf16x8*)(lds + PG8_SA(b, h) + aoff + m * 2048 + k * 1024); } while (0)
; #define PG8_MMA(ai, bj, At, Bt) do { __builtin_amdgcn_s_setprio(1); _Pragma("unroll") for (int m = 0; m < 4; ++m) _Pragma("unroll") for (int n = 0; n < 2; ++n) _Pragma("unroll") for (int k = 0; k < 2; ++k) \
;         acc[ai][bj][m][n] = __builtin_amdgcn_mfma_f32_16x16x32_bf16(Bt[n][k], At[m][k], acc[ai][bj][m][n], 0, 0, 0); __builtin_amdgcn_s_setprio(0); } while (0)
; #define PG8_WAIT_V(n) asm volatile("s_waitcnt vmcnt(" #n ")" ::: "memory")
; #define PG8_WAIT_L(n) asm volatile("s_waitcnt lgkmcnt(" #n ")" ::: "memory")
; #define PG8_BAR __builtin_amdgcn_s_barrier()
; #define PG8_SCHED __builtin_amdgcn_sched_barrier(0)
; template <class Epi, class Sched, bool ALIGN_EPI = false, bool SP2 = false, bool AROWS128 = false>
; __device__ __forceinline__ void gemm_phase(PG8_LAS unsigned char* lds, const Gemm g, const Sched& S, const Epi& E) {
;     ...
;         for (int t = 0; t < nt; t += 2) {
;     ...
;             PG8_WAIT_V(8); PG8_WAIT_L(0); PG8_BAR; PG8_MMA(0, 0, At, B0); PG8_MMA(0, 1, At, B1); PG8_BAR; PG8_SCHED;
;             PG8_LDA(At, 1, 1); PG8_STAGE(PG8_SB(1, 0), b3, voffB); PG8_STAGE(PG8_SB(1, 1), b3 + hstep, voffB); PG8_STAGE(PG8_SA(1, 0), a3, voffA);
;             PG8_WAIT_V(8); PG8_WAIT_L(0); PG8_BAR; PG8_MMA(1, 0, At, B0); PG8_MMA(1, 1, At, B1); PG8_BAR; PG8_SCHED;
	s_setprio 1
	s_waitcnt lgkmcnt(0)
	v_mfma_f32_16x16x32_bf16 v[124:127], v[152:155], v[184:187], v[124:127]
	v_mfma_f32_16x16x32_bf16 v[120:123], v[160:163], v[184:187], v[120:123]
	v_mfma_f32_16x16x32_bf16 v[116:119], v[152:155], v[192:195], v[116:119]
	v_mfma_f32_16x16x32_bf16 v[108:111], v[160:163], v[192:195], v[108:111]
	v_mfma_f32_16x16x32_bf16 v[100:103], v[152:155], v[200:203], v[100:103]
	v_mfma_f32_16x16x32_bf16 v[92:95], v[160:163], v[200:203], v[92:95]
	v_mfma_f32_16x16x32_bf16 v[84:87], v[152:155], v[212:215], v[84:87]
	v_mfma_f32_16x16x32_bf16 v[76:79], v[160:163], v[212:215], v[76:79]
	v_mfma_f32_16x16x32_bf16 v[124:127], v[156:159], v[188:191], v[124:127]
	v_mfma_f32_16x16x32_bf16 v[120:123], v[164:167], v[188:191], v[120:123]
	v_mfma_f32_16x16x32_bf16 v[116:119], v[156:159], v[196:199], v[116:119]
	v_mfma_f32_16x16x32_bf16 v[108:111], v[164:167], v[196:199], v[108:111]
	v_mfma_f32_16x16x32_bf16 v[100:103], v[156:159], v[204:207], v[100:103]
	v_mfma_f32_16x16x32_bf16 v[92:95], v[164:167], v[204:207], v[92:95]
	v_mfma_f32_16x16x32_bf16 v[84:87], v[156:159], v[216:219], v[84:87]
	v_mfma_f32_16x16x32_bf16 v[76:79], v[164:167], v[216:219], v[76:79]
	s_setprio 0
	s_setprio 1
	v_mfma_f32_16x16x32_bf16 v[112:115], v[168:171], v[184:187], v[112:115]
	v_mfma_f32_16x16x32_bf16 v[104:107], v[176:179], v[184:187], v[104:107]
	v_mfma_f32_16x16x32_bf16 v[96:99], v[168:171], v[192:195], v[96:99]
	v_mfma_f32_16x16x32_bf16 v[88:91], v[176:179], v[192:195], v[88:91]
	v_mfma_f32_16x16x32_bf16 v[80:83], v[168:171], v[200:203], v[80:83]
	v_mfma_f32_16x16x32_bf16 v[72:75], v[176:179], v[200:203], v[72:75]
	v_mfma_f32_16x16x32_bf16 v[68:71], v[168:171], v[212:215], v[68:71]
	v_mfma_f32_16x16x32_bf16 v[64:67], v[176:179], v[212:215], v[64:67]
	v_mfma_f32_16x16x32_bf16 v[112:115], v[172:175], v[188:191], v[112:115]
	v_mfma_f32_16x16x32_bf16 v[104:107], v[180:183], v[188:191], v[104:107]
	v_mfma_f32_16x16x32_bf16 v[96:99], v[172:175], v[196:199], v[96:99]
	v_mfma_f32_16x16x32_bf16 v[88:91], v[180:183], v[196:199], v[88:91]
	v_mfma_f32_16x16x32_bf16 v[80:83], v[172:175], v[204:207], v[80:83]
	v_mfma_f32_16x16x32_bf16 v[72:75], v[180:183], v[204:207], v[72:75]
	v_mfma_f32_16x16x32_bf16 v[68:71], v[172:175], v[216:219], v[68:71]
	v_mfma_f32_16x16x32_bf16 v[64:67], v[180:183], v[216:219], v[64:67]
	s_setprio 0
	s_barrier
	s_add_i32 s48, s78, s3
	v_lshl_add_u64 v[144:145], v[144:145], 0, s[8:9]
	s_mov_b32 m0, s48
	ds_read_b128 v[184:187], v151 offset:49152
	ds_read_b128 v[188:191], v151 offset:50176
	ds_read_b128 v[192:195], v151 offset:51200
	ds_read_b128 v[196:199], v151 offset:52224
	ds_read_b128 v[200:203], v151 offset:53248
	ds_read_b128 v[204:207], v151 offset:54272
	ds_read_b128 v[212:215], v151 offset:55296
	ds_read_b128 v[216:219], v151 offset:56320
	global_load_lds_dwordx4 v[144:145], off
	s_add_i32 m0, s48, 0x2000
	s_add_u32 s38, s38, 0x100080
	v_lshl_add_u64 v[144:145], v[208:209], 0, s[8:9]
	s_addc_u32 s39, s39, 0
	s_add_i32 s48, s79, s3
	global_load_lds_dwordx4 v[144:145], off
	v_lshl_add_u64 v[144:145], s[38:39], 0, v[132:133]
	s_mov_b32 m0, s48
	s_nop 0
	global_load_lds_dwordx4 v[144:145], off
	v_lshl_add_u64 v[144:145], s[38:39], 0, v[128:129]
	s_add_i32 m0, s48, 0x2000
	s_nop 0
	global_load_lds_dwordx4 v[144:145], off
	s_waitcnt vmcnt(6)
	s_waitcnt lgkmcnt(0)
	s_barrier
	s_setprio 1
	s_waitcnt lgkmcnt(0)
	v_mfma_f32_16x16x32_bf16 v[60:63], v[152:155], v[184:187], v[60:63]
	v_mfma_f32_16x16x32_bf16 v[56:59], v[160:163], v[184:187], v[56:59]
	v_mfma_f32_16x16x32_bf16 v[52:55], v[152:155], v[192:195], v[52:55]
	v_mfma_f32_16x16x32_bf16 v[44:47], v[160:163], v[192:195], v[44:47]
	v_mfma_f32_16x16x32_bf16 v[36:39], v[152:155], v[200:203], v[36:39]
	v_mfma_f32_16x16x32_bf16 v[28:31], v[160:163], v[200:203], v[28:31]
	v_mfma_f32_16x16x32_bf16 v[20:23], v[152:155], v[212:215], v[20:23]
	v_mfma_f32_16x16x32_bf16 v[12:15], v[160:163], v[212:215], v[12:15]
	v_mfma_f32_16x16x32_bf16 v[60:63], v[156:159], v[188:191], v[60:63]
	v_mfma_f32_16x16x32_bf16 v[56:59], v[164:167], v[188:191], v[56:59]
	v_mfma_f32_16x16x32_bf16 v[52:55], v[156:159], v[196:199], v[52:55]
	v_mfma_f32_16x16x32_bf16 v[44:47], v[164:167], v[196:199], v[44:47]
	v_mfma_f32_16x16x32_bf16 v[36:39], v[156:159], v[204:207], v[36:39]
	v_mfma_f32_16x16x32_bf16 v[28:31], v[164:167], v[204:207], v[28:31]
	v_mfma_f32_16x16x32_bf16 v[20:23], v[156:159], v[216:219], v[20:23]
	v_mfma_f32_16x16x32_bf16 v[12:15], v[164:167], v[216:219], v[12:15]
	s_setprio 0
	s_setprio 1
	v_mfma_f32_16x16x32_bf16 v[48:51], v[168:171], v[184:187], v[48:51]
	v_mfma_f32_16x16x32_bf16 v[40:43], v[176:179], v[184:187], v[40:43]
	v_mfma_f32_16x16x32_bf16 v[32:35], v[168:171], v[192:195], v[32:35]
	v_mfma_f32_16x16x32_bf16 v[24:27], v[176:179], v[192:195], v[24:27]
	v_mfma_f32_16x16x32_bf16 v[16:19], v[168:171], v[200:203], v[16:19]
	v_mfma_f32_16x16x32_bf16 v[8:11], v[176:179], v[200:203], v[8:11]
	v_mfma_f32_16x16x32_bf16 v[4:7], v[168:171], v[212:215], v[4:7]
	v_mfma_f32_16x16x32_bf16 v[0:3], v[176:179], v[212:215], v[0:3]
	v_mfma_f32_16x16x32_bf16 v[48:51], v[172:175], v[188:191], v[48:51]
	v_mfma_f32_16x16x32_bf16 v[40:43], v[180:183], v[188:191], v[40:43]
	v_mfma_f32_16x16x32_bf16 v[32:35], v[172:175], v[196:199], v[32:35]
	v_mfma_f32_16x16x32_bf16 v[24:27], v[180:183], v[196:199], v[24:27]
	v_mfma_f32_16x16x32_bf16 v[16:19], v[172:175], v[204:207], v[16:19]
	v_mfma_f32_16x16x32_bf16 v[8:11], v[180:183], v[204:207], v[8:11]
	v_mfma_f32_16x16x32_bf16 v[4:7], v[172:175], v[216:219], v[4:7]
	v_mfma_f32_16x16x32_bf16 v[0:3], v[180:183], v[216:219], v[0:3]
	s_setprio 0
	s_barrier
	s_add_i32 s77, s77, 2
	s_add_u32 s36, s36, 0x100
	s_addc_u32 s37, s37, 0
	s_add_u32 s73, s73, 0x100
	s_addc_u32 s76, s76, 0
	s_cmp_gt_u32 s77, 61
	s_cbranch_scc0 .LBB0_752
	s_and_b64 vcc, exec, s[10:11]
	s_cbranch_vccz .LBB0_755
	s_barrier

; __global__ void __launch_bounds__(NWAVES * 64, 2) hymba_fwd(Args args) {
	.amdhsa_kernel _Z9hymba_fwd4Args
		.amdhsa_group_segment_fixed_size 0
		.amdhsa_private_segment_fixed_size 0
		.amdhsa_kernarg_size 496
		.amdhsa_user_sgpr_count 2
		.amdhsa_user_sgpr_dispatch_ptr 0
		.amdhsa_user_sgpr_queue_ptr 0
		.amdhsa_user_sgpr_kernarg_segment_ptr 1
		.amdhsa_user_sgpr_dispatch_id 0
		.amdhsa_user_sgpr_kernarg_preload_length 0
		.amdhsa_user_sgpr_kernarg_preload_offset 0
		.amdhsa_user_sgpr_private_segment_size 0
		.amdhsa_uses_dynamic_stack 0
		.amdhsa_enable_private_segment 0
		.amdhsa_system_sgpr_workgroup_id_x 1
		.amdhsa_system_sgpr_workgroup_id_y 0
		.amdhsa_system_sgpr_workgroup_id_z 0
		.amdhsa_system_sgpr_workgroup_info 0
		.amdhsa_system_vgpr_workitem_id 2
		.amdhsa_next_free_vgpr 256
		.amdhsa_next_free_sgpr 102
		.amdhsa_accum_offset 256
		.amdhsa_reserve_vcc 1
		.amdhsa_float_round_mode_32 0
		.amdhsa_float_round_mode_16_64 0
		.amdhsa_float_denorm_mode_32 3
		.amdhsa_float_denorm_mode_16_64 3
		.amdhsa_dx10_clamp 1
		.amdhsa_ieee_mode 1
		.amdhsa_fp16_overflow 0
		.amdhsa_tg_split 0
		.amdhsa_exception_fp_ieee_invalid_op 0
		.amdhsa_exception_fp_denorm_src 0
		.amdhsa_exception_fp_ieee_div_zero 0
		.amdhsa_exception_fp_ieee_overflow 0
		.amdhsa_exception_fp_ieee_underflow 0
		.amdhsa_exception_fp_ieee_inexact 0
		.amdhsa_exception_int_div_zero 0
	.end_amdhsa_kernel

; __global__ void __launch_bounds__(NWAVES * 64, 2) hymba_fwd(Args args) {
amdhsa.kernels:
  - .agpr_count:     0
    .args:
      - .offset:         0
        .size:           240
        .value_kind:     by_value
      - .offset:         240
        .size:           4
        .value_kind:     hidden_block_count_x
      - .offset:         244
        .size:           4
        .value_kind:     hidden_block_count_y
      - .offset:         248
        .size:           4
        .value_kind:     hidden_block_count_z
      - .offset:         252
        .size:           2
        .value_kind:     hidden_group_size_x
      - .offset:         254
        .size:           2
        .value_kind:     hidden_group_size_y
      - .offset:         256
        .size:           2
        .value_kind:     hidden_group_size_z
      - .offset:         258
        .size:           2
        .value_kind:     hidden_remainder_x
      - .offset:         260
        .size:           2
        .value_kind:     hidden_remainder_y
      - .offset:         262
        .size:           2
        .value_kind:     hidden_remainder_z
      - .offset:         280
        .size:           8
        .value_kind:     hidden_global_offset_x
      - .offset:         288
        .size:           8
        .value_kind:     hidden_global_offset_y
      - .offset:         296
        .size:           8
        .value_kind:     hidden_global_offset_z
      - .offset:         304
        .size:           2
        .value_kind:     hidden_grid_dims
      - .offset:         328
        .size:           8
        .value_kind:     hidden_multigrid_sync_arg
      - .offset:         360
        .size:           4
        .value_kind:     hidden_dynamic_lds_size
    .group_segment_fixed_size: 0
    .kernarg_segment_align: 8
    .kernarg_segment_size: 496
    .language:       OpenCL C
    .language_version:
      - 2
      - 0
    .max_flat_workgroup_size: 512
    .name:           _Z9hymba_fwd4Args
    .private_segment_fixed_size: 0
    .sgpr_count:     108
    .sgpr_spill_count: 17
    .symbol:         _Z9hymba_fwd4Args.kd
    .uniform_work_group_size: 1
    .uses_dynamic_stack: false
    .vgpr_count:     256
    .vgpr_spill_count: 0
    .wavefront_size: 64
